# accumulator zeroing per GEMM unit with 63 v_mov_b64 instead of 127 v_mov_b32
# speedup vs baseline: 1.0050x; 1.0050x over previous
; template <class Epi, class Sched, bool ALIGN_EPI = false, bool SP2 = false>
; __device__ __forceinline__ void gemm_phase(PG8_LAS unsigned char* lds, const Gemm g, const Sched& S, const Epi& E, const int wave_) {
;     ...
;         const bool has_next = S.next(ui + 1, nxt);
;         const char* nA = has_next ? (const char*)g.A + (size_t)nxt.pm * tstep : cA; const char* nB = has_next ? (const char*)g.Bt + (size_t)nxt.pn * tstep : cB;
;     ...
; #pragma unroll
;         for (int a = 0; a < 2; ++a)
; #pragma unroll
;             for (int b = 0; b < 2; ++b)
; #pragma unroll
;                 for (int m = 0; m < 4; ++m)
; #pragma unroll
;                     for (int n = 0; n < 2; ++n) acc[a][b][m][n] = (f32x4){0.f, 0.f, 0.f, 0.f};
.LBB0_128:
	s_ashr_i32 s39, s38, 31
	s_lshl_b64 s[22:23], s[38:39], 20
	v_readlane_b32 s24, v248, 27
	v_readlane_b32 s25, v248, 28
	s_add_u32 s40, s24, s22
	s_addc_u32 s41, s25, s23
	s_and_b64 s[22:23], s[16:17], exec
	s_cselect_b32 s19, s41, s47
	s_cselect_b32 s39, s40, s46
	s_ashr_i32 s37, s36, 31
	s_lshl_b64 s[22:23], s[36:37], 20
	v_readlane_b32 s24, v248, 25
	v_readlane_b32 s25, v248, 26
	s_add_u32 s42, s24, s22
	s_addc_u32 s43, s25, s23
	s_and_b64 s[22:23], s[16:17], exec
	s_cselect_b32 s37, s43, s49
	s_cselect_b32 vcc_lo, s42, s48
	s_add_u32 s46, s46, 0x80080
	s_addc_u32 s47, s47, 0
	s_add_u32 vcc_hi, s48, 0x100
	v_mov_b32_e32 v0, 0
	s_addc_u32 s97, s49, 0
	s_mov_b32 s22, -2
	v_mov_b32_e32 v1, 0
	v_mov_b64_e32 v[2:3], 0
	v_mov_b64_e32 v[4:5], 0
	v_mov_b64_e32 v[6:7], 0
	v_mov_b64_e32 v[8:9], 0
	v_mov_b64_e32 v[10:11], 0
	v_mov_b64_e32 v[12:13], 0
	v_mov_b64_e32 v[14:15], 0
	v_mov_b64_e32 v[16:17], 0
	v_mov_b64_e32 v[18:19], 0
	v_mov_b64_e32 v[20:21], 0
	v_mov_b64_e32 v[22:23], 0
	v_mov_b64_e32 v[24:25], 0
	v_mov_b64_e32 v[26:27], 0
	v_mov_b64_e32 v[28:29], 0
	v_mov_b64_e32 v[30:31], 0
	v_mov_b64_e32 v[32:33], 0
	v_mov_b64_e32 v[34:35], 0
	v_mov_b64_e32 v[36:37], 0
	v_mov_b64_e32 v[38:39], 0
	v_mov_b64_e32 v[40:41], 0
	v_mov_b64_e32 v[42:43], 0
	v_mov_b64_e32 v[44:45], 0
	v_mov_b64_e32 v[46:47], 0
	v_mov_b64_e32 v[48:49], 0
	v_mov_b64_e32 v[50:51], 0
	v_mov_b64_e32 v[52:53], 0
	v_mov_b64_e32 v[54:55], 0
	v_mov_b64_e32 v[56:57], 0
	v_mov_b64_e32 v[58:59], 0
	v_mov_b64_e32 v[60:61], 0
	v_mov_b64_e32 v[62:63], 0
	v_mov_b64_e32 v[64:65], 0
	v_mov_b64_e32 v[66:67], 0
	v_mov_b64_e32 v[68:69], 0
	v_mov_b64_e32 v[70:71], 0
	v_mov_b64_e32 v[72:73], 0
	v_mov_b64_e32 v[74:75], 0
	v_mov_b64_e32 v[76:77], 0
	v_mov_b64_e32 v[78:79], 0
	v_mov_b64_e32 v[80:81], 0
	v_mov_b64_e32 v[82:83], 0
	v_mov_b64_e32 v[84:85], 0
	v_mov_b64_e32 v[86:87], 0
	v_mov_b64_e32 v[88:89], 0
	v_mov_b64_e32 v[90:91], 0
	v_mov_b64_e32 v[92:93], 0
	v_mov_b64_e32 v[94:95], 0
	v_mov_b64_e32 v[96:97], 0
	v_mov_b64_e32 v[98:99], 0
	v_mov_b64_e32 v[100:101], 0
	v_mov_b64_e32 v[102:103], 0
	v_mov_b64_e32 v[104:105], 0
	v_mov_b64_e32 v[106:107], 0
	v_mov_b64_e32 v[108:109], 0
	v_mov_b64_e32 v[110:111], 0
	v_mov_b64_e32 v[112:113], 0
	v_mov_b64_e32 v[114:115], 0
	v_mov_b64_e32 v[116:117], 0
	v_mov_b64_e32 v[118:119], 0
	v_mov_b64_e32 v[120:121], 0
	v_mov_b64_e32 v[122:123], 0
	v_mov_b64_e32 v[124:125], 0
	v_mov_b64_e32 v[126:127], 0

; template <class Epi, class Sched, bool ALIGN_EPI = false, bool SP2 = false>
; __device__ __forceinline__ void gemm_phase(PG8_LAS unsigned char* lds, const Gemm g, const Sched& S, const Epi& E, const int wave_) {
;     ...
;         const bool has_next = S.next(ui + 1, nxt);
;         const char* nA = has_next ? (const char*)g.A + (size_t)nxt.pm * tstep : cA; const char* nB = has_next ? (const char*)g.Bt + (size_t)nxt.pn * tstep : cB;
;     ...
; #pragma unroll
;         for (int a = 0; a < 2; ++a)
; #pragma unroll
;             for (int b = 0; b < 2; ++b)
; #pragma unroll
;                 for (int m = 0; m < 4; ++m)
; #pragma unroll
;                     for (int n = 0; n < 2; ++n) acc[a][b][m][n] = (f32x4){0.f, 0.f, 0.f, 0.f};
.LBB0_401:
	s_ashr_i32 s19, s18, 31
	s_lshl_b64 s[20:21], s[18:19], 21
	v_readlane_b32 s22, v248, 25
	v_readlane_b32 s23, v248, 26
	s_add_u32 s20, s22, s20
	s_addc_u32 s21, s23, s21
	s_and_b64 s[22:23], s[4:5], exec
	s_cselect_b32 s19, s21, s29
	s_cselect_b32 s25, s20, s28
	s_ashr_i32 s17, s16, 31
	s_lshl_b64 s[22:23], s[16:17], 21
	v_readlane_b32 s34, v248, 29
	v_readlane_b32 s35, v248, 30
	s_add_u32 s22, s34, s22
	s_addc_u32 s23, s35, s23
	s_and_b64 s[34:35], s[4:5], exec
	s_cselect_b32 s17, s23, s31
	s_cselect_b32 s50, s22, s30
	s_add_u32 s28, s28, 0x100080
	s_addc_u32 s29, s29, 0
	s_add_u32 s51, s30, 0x100
	v_mov_b32_e32 v0, 0
	s_addc_u32 s52, s31, 0
	s_mov_b32 s53, -2
	s_waitcnt lgkmcnt(0)
	v_mov_b32_e32 v1, 0
	v_mov_b64_e32 v[2:3], 0
	v_mov_b64_e32 v[4:5], 0
	v_mov_b64_e32 v[6:7], 0
	v_mov_b64_e32 v[8:9], 0
	v_mov_b64_e32 v[10:11], 0
	v_mov_b64_e32 v[12:13], 0
	v_mov_b64_e32 v[14:15], 0
	v_mov_b64_e32 v[16:17], 0
	v_mov_b64_e32 v[18:19], 0
	v_mov_b64_e32 v[20:21], 0
	v_mov_b64_e32 v[22:23], 0
	v_mov_b64_e32 v[24:25], 0
	v_mov_b64_e32 v[26:27], 0
	v_mov_b64_e32 v[28:29], 0
	v_mov_b64_e32 v[30:31], 0
	v_mov_b64_e32 v[32:33], 0
	v_mov_b64_e32 v[34:35], 0
	v_mov_b64_e32 v[36:37], 0
	v_mov_b64_e32 v[38:39], 0
	v_mov_b64_e32 v[40:41], 0
	v_mov_b64_e32 v[42:43], 0
	v_mov_b64_e32 v[44:45], 0
	v_mov_b64_e32 v[46:47], 0
	v_mov_b64_e32 v[48:49], 0
	v_mov_b64_e32 v[50:51], 0
	v_mov_b64_e32 v[52:53], 0
	v_mov_b64_e32 v[54:55], 0
	v_mov_b64_e32 v[56:57], 0
	v_mov_b64_e32 v[58:59], 0
	v_mov_b64_e32 v[60:61], 0
	v_mov_b64_e32 v[62:63], 0
	v_mov_b64_e32 v[64:65], 0
	v_mov_b64_e32 v[66:67], 0
	v_mov_b64_e32 v[68:69], 0
	v_mov_b64_e32 v[70:71], 0
	v_mov_b64_e32 v[72:73], 0
	v_mov_b64_e32 v[74:75], 0
	v_mov_b64_e32 v[76:77], 0
	v_mov_b64_e32 v[78:79], 0
	v_mov_b64_e32 v[80:81], 0
	v_mov_b64_e32 v[82:83], 0
	v_mov_b64_e32 v[84:85], 0
	v_mov_b64_e32 v[86:87], 0
	v_mov_b64_e32 v[88:89], 0
	v_mov_b64_e32 v[90:91], 0
	v_mov_b64_e32 v[92:93], 0
	v_mov_b64_e32 v[94:95], 0
	v_mov_b64_e32 v[96:97], 0
	v_mov_b64_e32 v[98:99], 0
	v_mov_b64_e32 v[100:101], 0
	v_mov_b64_e32 v[102:103], 0
	v_mov_b64_e32 v[104:105], 0
	v_mov_b64_e32 v[106:107], 0
	v_mov_b64_e32 v[108:109], 0
	v_mov_b64_e32 v[110:111], 0
	v_mov_b64_e32 v[112:113], 0
	v_mov_b64_e32 v[114:115], 0
	v_mov_b64_e32 v[116:117], 0
	v_mov_b64_e32 v[118:119], 0
	v_mov_b64_e32 v[120:121], 0
	v_mov_b64_e32 v[122:123], 0
	v_mov_b64_e32 v[124:125], 0
	v_mov_b64_e32 v[126:127], 0

; template <class Epi, class Sched, bool ALIGN_EPI = false, bool SP2 = false>
; __device__ __forceinline__ void gemm_phase(PG8_LAS unsigned char* lds, const Gemm g, const Sched& S, const Epi& E, const int wave_) {
;     ...
;         const bool has_next = S.next(ui + 1, nxt);
;         const char* nA = has_next ? (const char*)g.A + (size_t)nxt.pm * tstep : cA; const char* nB = has_next ? (const char*)g.Bt + (size_t)nxt.pn * tstep : cB;
;     ...
; #pragma unroll
;         for (int a = 0; a < 2; ++a)
; #pragma unroll
;             for (int b = 0; b < 2; ++b)
; #pragma unroll
;                 for (int m = 0; m < 4; ++m)
; #pragma unroll
;                     for (int n = 0; n < 2; ++n) acc[a][b][m][n] = (f32x4){0.f, 0.f, 0.f, 0.f};
.LBB0_494:
	s_ashr_i32 s29, s28, 31
	s_lshl_b64 s[30:31], s[28:29], 20
	s_add_u32 s30, s38, s30
	s_addc_u32 s31, s39, s31
	s_and_b64 s[34:35], s[0:1], exec
	s_cselect_b32 s5, s31, s37
	s_cselect_b32 s7, s30, s36
	s_ashr_i32 s27, s26, 31
	s_lshl_b64 s[34:35], s[26:27], 20
	v_readlane_b32 s42, v248, 31
	v_readlane_b32 s43, v248, 32
	s_add_u32 s34, s42, s34
	s_addc_u32 s35, s43, s35
	s_and_b64 s[42:43], s[0:1], exec
	s_cselect_b32 s27, s35, s41
	s_cselect_b32 s29, s34, s40
	s_add_u32 s36, s36, 0x80080
	s_addc_u32 s37, s37, 0
	s_add_u32 s61, s40, 0x100
	v_mov_b32_e32 v0, 0
	s_addc_u32 s62, s41, 0
	s_mov_b32 s63, -2
	v_mov_b32_e32 v1, 0
	v_mov_b64_e32 v[2:3], 0
	v_mov_b64_e32 v[4:5], 0
	v_mov_b64_e32 v[6:7], 0
	v_mov_b64_e32 v[8:9], 0
	v_mov_b64_e32 v[10:11], 0
	v_mov_b64_e32 v[12:13], 0
	v_mov_b64_e32 v[14:15], 0
	v_mov_b64_e32 v[16:17], 0
	v_mov_b64_e32 v[18:19], 0
	v_mov_b64_e32 v[20:21], 0
	v_mov_b64_e32 v[22:23], 0
	v_mov_b64_e32 v[24:25], 0
	v_mov_b64_e32 v[26:27], 0
	v_mov_b64_e32 v[28:29], 0
	v_mov_b64_e32 v[30:31], 0
	v_mov_b64_e32 v[32:33], 0
	v_mov_b64_e32 v[34:35], 0
	v_mov_b64_e32 v[36:37], 0
	v_mov_b64_e32 v[38:39], 0
	v_mov_b64_e32 v[40:41], 0
	v_mov_b64_e32 v[42:43], 0
	v_mov_b64_e32 v[44:45], 0
	v_mov_b64_e32 v[46:47], 0
	v_mov_b64_e32 v[48:49], 0
	v_mov_b64_e32 v[50:51], 0
	v_mov_b64_e32 v[52:53], 0
	v_mov_b64_e32 v[54:55], 0
	v_mov_b64_e32 v[56:57], 0
	v_mov_b64_e32 v[58:59], 0
	v_mov_b64_e32 v[60:61], 0
	v_mov_b64_e32 v[62:63], 0
	v_mov_b64_e32 v[64:65], 0
	v_mov_b64_e32 v[66:67], 0
	v_mov_b64_e32 v[68:69], 0
	v_mov_b64_e32 v[70:71], 0
	v_mov_b64_e32 v[72:73], 0
	v_mov_b64_e32 v[74:75], 0
	v_mov_b64_e32 v[76:77], 0
	v_mov_b64_e32 v[78:79], 0
	v_mov_b64_e32 v[80:81], 0
	v_mov_b64_e32 v[82:83], 0
	v_mov_b64_e32 v[84:85], 0
	v_mov_b64_e32 v[86:87], 0
	v_mov_b64_e32 v[88:89], 0
	v_mov_b64_e32 v[90:91], 0
	v_mov_b64_e32 v[92:93], 0
	v_mov_b64_e32 v[94:95], 0
	v_mov_b64_e32 v[96:97], 0
	v_mov_b64_e32 v[98:99], 0
	v_mov_b64_e32 v[100:101], 0
	v_mov_b64_e32 v[102:103], 0
	v_mov_b64_e32 v[104:105], 0
	v_mov_b64_e32 v[106:107], 0
	v_mov_b64_e32 v[108:109], 0
	v_mov_b64_e32 v[110:111], 0
	v_mov_b64_e32 v[112:113], 0
	v_mov_b64_e32 v[114:115], 0
	v_mov_b64_e32 v[116:117], 0
	v_mov_b64_e32 v[118:119], 0
	v_mov_b64_e32 v[120:121], 0
	v_mov_b64_e32 v[122:123], 0
	v_mov_b64_e32 v[124:125], 0
	v_mov_b64_e32 v[126:127], 0

; template <class Epi, class Sched, bool ALIGN_EPI = false, bool SP2 = false>
; __device__ __forceinline__ void gemm_phase(PG8_LAS unsigned char* lds, const Gemm g, const Sched& S, const Epi& E, const int wave_) {
;     ...
;         const bool has_next = S.next(ui + 1, nxt);
;         const char* nA = has_next ? (const char*)g.A + (size_t)nxt.pm * tstep : cA; const char* nB = has_next ? (const char*)g.Bt + (size_t)nxt.pn * tstep : cB;
;     ...
; #pragma unroll
;         for (int a = 0; a < 2; ++a)
; #pragma unroll
;             for (int b = 0; b < 2; ++b)
; #pragma unroll
;                 for (int m = 0; m < 4; ++m)
; #pragma unroll
;                     for (int n = 0; n < 2; ++n) acc[a][b][m][n] = (f32x4){0.f, 0.f, 0.f, 0.f};
.LBB0_699:
	s_ashr_i32 s23, s22, 31
	s_lshl_b64 s[24:25], s[22:23], 20
	v_readlane_b32 s26, v248, 25
	v_readlane_b32 s27, v248, 26
	s_add_u32 s24, s26, s24
	s_addc_u32 s25, s27, s25
	s_and_b64 s[26:27], s[6:7], exec
	s_cselect_b32 s23, s25, s35
	s_cselect_b32 s29, s24, s34
	s_ashr_i32 s21, s20, 31
	s_lshl_b64 s[26:27], s[20:21], 20
	s_add_u32 s26, s62, s26
	s_addc_u32 s27, s63, s27
	s_and_b64 s[40:41], s[6:7], exec
	s_cselect_b32 s21, s27, s37
	s_cselect_b32 s31, s26, s36
	s_add_u32 s34, s34, 0x80080
	s_addc_u32 s35, s35, 0
	s_add_u32 s56, s36, 0x100
	v_mov_b32_e32 v0, 0
	s_addc_u32 s57, s37, 0
	s_mov_b32 s58, -2
	v_mov_b32_e32 v1, 0
	v_mov_b64_e32 v[2:3], 0
	v_mov_b64_e32 v[4:5], 0
	v_mov_b64_e32 v[6:7], 0
	v_mov_b64_e32 v[8:9], 0
	v_mov_b64_e32 v[10:11], 0
	v_mov_b64_e32 v[12:13], 0
	v_mov_b64_e32 v[14:15], 0
	v_mov_b64_e32 v[16:17], 0
	v_mov_b64_e32 v[18:19], 0
	v_mov_b64_e32 v[20:21], 0
	v_mov_b64_e32 v[22:23], 0
	v_mov_b64_e32 v[24:25], 0
	v_mov_b64_e32 v[26:27], 0
	v_mov_b64_e32 v[28:29], 0
	v_mov_b64_e32 v[30:31], 0
	v_mov_b64_e32 v[32:33], 0
	v_mov_b64_e32 v[34:35], 0
	v_mov_b64_e32 v[36:37], 0
	v_mov_b64_e32 v[38:39], 0
	v_mov_b64_e32 v[40:41], 0
	v_mov_b64_e32 v[42:43], 0
	v_mov_b64_e32 v[44:45], 0
	v_mov_b64_e32 v[46:47], 0
	v_mov_b64_e32 v[48:49], 0
	v_mov_b64_e32 v[50:51], 0
	v_mov_b64_e32 v[52:53], 0
	v_mov_b64_e32 v[54:55], 0
	v_mov_b64_e32 v[56:57], 0
	v_mov_b64_e32 v[58:59], 0
	v_mov_b64_e32 v[60:61], 0
	v_mov_b64_e32 v[62:63], 0
	v_mov_b64_e32 v[64:65], 0
	v_mov_b64_e32 v[66:67], 0
	v_mov_b64_e32 v[68:69], 0
	v_mov_b64_e32 v[70:71], 0
	v_mov_b64_e32 v[72:73], 0
	v_mov_b64_e32 v[74:75], 0
	v_mov_b64_e32 v[76:77], 0
	v_mov_b64_e32 v[78:79], 0
	v_mov_b64_e32 v[80:81], 0
	v_mov_b64_e32 v[82:83], 0
	v_mov_b64_e32 v[84:85], 0
	v_mov_b64_e32 v[86:87], 0
	v_mov_b64_e32 v[88:89], 0
	v_mov_b64_e32 v[90:91], 0
	v_mov_b64_e32 v[92:93], 0
	v_mov_b64_e32 v[94:95], 0
	v_mov_b64_e32 v[96:97], 0
	v_mov_b64_e32 v[98:99], 0
	v_mov_b64_e32 v[100:101], 0
	v_mov_b64_e32 v[102:103], 0
	v_mov_b64_e32 v[104:105], 0
	v_mov_b64_e32 v[106:107], 0
	v_mov_b64_e32 v[108:109], 0
	v_mov_b64_e32 v[110:111], 0
	v_mov_b64_e32 v[112:113], 0
	v_mov_b64_e32 v[114:115], 0
	v_mov_b64_e32 v[116:117], 0
	v_mov_b64_e32 v[118:119], 0
	v_mov_b64_e32 v[120:121], 0
	v_mov_b64_e32 v[122:123], 0
	v_mov_b64_e32 v[124:125], 0
	v_mov_b64_e32 v[126:127], 0
